# w_out0 transposes deferred from P0 now run on the 64 memory-KV workgroups at the head of P3 instead of the odd-XCD GLU workgroups
# speedup vs baseline: 1.0022x; 1.0022x over previous
.LBB0_386:
	s_or_b64 exec, exec, s[0:1]
	s_cmpk_lt_i32 s2, 0xc0
	s_cbranch_scc1 .Ldf_skip_p3
	v_writelane_b32 v234, s0, 0
	v_writelane_b32 v234, s1, 1
	v_writelane_b32 v234, s2, 2
	v_writelane_b32 v234, s3, 3
	v_writelane_b32 v234, s4, 4
	v_writelane_b32 v234, s5, 5
	v_writelane_b32 v234, s6, 6
	v_writelane_b32 v234, s7, 7
	v_writelane_b32 v234, s8, 8
	v_writelane_b32 v234, s9, 9
	v_writelane_b32 v234, s10, 10
	v_writelane_b32 v234, s11, 11
	v_writelane_b32 v234, s12, 12
	v_writelane_b32 v234, s13, 13
	v_writelane_b32 v234, s14, 14
	v_writelane_b32 v234, s15, 15
	v_writelane_b32 v234, s16, 16
	v_writelane_b32 v234, s17, 17
	v_writelane_b32 v234, s18, 18
	v_writelane_b32 v234, s19, 19
	v_writelane_b32 v234, s20, 20
	v_writelane_b32 v234, s21, 21
	v_writelane_b32 v234, s22, 22
	v_writelane_b32 v234, s23, 23
	v_writelane_b32 v234, s24, 24
	v_writelane_b32 v234, s25, 25
	v_writelane_b32 v234, s26, 26
	v_writelane_b32 v234, s27, 27
	v_writelane_b32 v234, s28, 28
	v_writelane_b32 v234, s29, 29
	v_writelane_b32 v234, s30, 30
	v_writelane_b32 v234, s31, 31
	v_writelane_b32 v234, s32, 32
	v_writelane_b32 v234, s33, 33
	v_writelane_b32 v234, s34, 34
	v_writelane_b32 v234, s35, 35
	v_writelane_b32 v234, s36, 36
	v_writelane_b32 v234, s37, 37
	v_writelane_b32 v234, s38, 38
	v_writelane_b32 v234, s39, 39
	v_writelane_b32 v234, s40, 40
	v_writelane_b32 v234, s41, 41
	v_writelane_b32 v234, s42, 42
	v_writelane_b32 v234, s43, 43
	v_writelane_b32 v234, s44, 44
	v_writelane_b32 v234, s45, 45
	v_writelane_b32 v234, s46, 46
	v_writelane_b32 v234, s47, 47
	v_writelane_b32 v234, s48, 48
	v_writelane_b32 v234, s49, 49
	v_writelane_b32 v234, s50, 50
	v_writelane_b32 v234, s51, 51
	v_writelane_b32 v234, s52, 52
	v_writelane_b32 v234, s53, 53
	v_writelane_b32 v234, s54, 54
	v_writelane_b32 v234, s55, 55
	v_writelane_b32 v234, s56, 56
	v_writelane_b32 v234, s57, 57
	v_writelane_b32 v234, s58, 58
	v_writelane_b32 v234, s59, 59
	v_writelane_b32 v234, s60, 60
	v_writelane_b32 v234, s61, 61
	v_writelane_b32 v234, s62, 62
	v_writelane_b32 v234, s63, 63
	v_writelane_b32 v235, s64, 0
	v_writelane_b32 v235, s65, 1
	v_writelane_b32 v235, s66, 2
	v_writelane_b32 v235, s67, 3
	v_writelane_b32 v235, s68, 4
	v_writelane_b32 v235, s69, 5
	v_writelane_b32 v235, s70, 6
	v_writelane_b32 v235, s71, 7
	v_writelane_b32 v235, s72, 8
	v_writelane_b32 v235, s73, 9
	v_writelane_b32 v235, s74, 10
	v_writelane_b32 v235, s75, 11
	v_writelane_b32 v235, s76, 12
	v_writelane_b32 v235, s77, 13
	v_writelane_b32 v235, s78, 14
	v_writelane_b32 v235, s79, 15
	v_writelane_b32 v235, s80, 16
	v_writelane_b32 v235, s81, 17
	v_writelane_b32 v235, s82, 18
	v_writelane_b32 v235, s83, 19
	v_writelane_b32 v235, s84, 20
	v_writelane_b32 v235, s85, 21
	v_writelane_b32 v235, s86, 22
	v_writelane_b32 v235, s87, 23
	v_writelane_b32 v235, s88, 24
	v_writelane_b32 v235, s89, 25
	v_writelane_b32 v235, s90, 26
	v_writelane_b32 v235, s91, 27
	v_writelane_b32 v235, s92, 28
	v_writelane_b32 v235, s93, 29
	v_writelane_b32 v235, s94, 30
	v_writelane_b32 v235, s95, 31
	v_writelane_b32 v235, s96, 32
	v_writelane_b32 v235, s97, 33
	v_writelane_b32 v235, vcc_lo, 34
	v_writelane_b32 v235, vcc_hi, 35
	v_readlane_b32 s72, v233, 47
	v_readlane_b32 s73, v233, 48
	v_readlane_b32 s74, v233, 49
	v_readlane_b32 s75, v233, 50
	v_readlane_b32 s76, v233, 51
	v_readlane_b32 s77, v233, 52
	s_add_u32 s62, s92, 0x400000
	s_addc_u32 s63, s93, 0
	v_mov_b32_e32 v1, v210
	s_nop 0
	v_readfirstlane_b32 s0, v1
	v_and_b32_e32 v76, 63, v1
	s_nop 3
	s_ashr_i32 s8, s0, 6
	s_sub_i32 s1, s2, 0xc0
	s_lshl_b32 s1, s1, 3
	s_add_i32 s26, s8, s1
	s_addk_i32 s26, 0x1c80
	s_movk_i32 s96, 0x200
	s_movk_i32 s101, 0x247f
	s_mov_b32 s100, 2
	s_branch .Lp0_setup
